# phase 2 loop software-pipelined: next token's row loads issued at the top of the current token (free VGPRs v60-81), same arithmetic
# speedup vs baseline: 1.0043x; 1.0043x over previous
.LBB0_372:
	s_cmp_lt_i32 s74, 3
	s_waitcnt lgkmcnt(0)
	s_cselect_b64 s[16:17], -1, 0
	s_and_b64 s[0:1], s[16:17], s[0:1]
	s_andn2_b64 vcc, exec, s[0:1]
	s_cbranch_vccnz .LBB0_418
	v_readlane_b32 s0, v254, 29
	s_cmpk_gt_i32 s0, 0x7fff
	s_movk_i32 s11, 0x7fff
	v_readlane_b32 s1, v254, 30
	s_cbranch_scc1 .LBB0_418
	v_mov_b32_e32 v0, 0x600
	v_lshl_or_b32 v24, v181, 3, v0
	v_cmp_gt_u32_e32 vcc, 36, v181
	v_readlane_b32 s52, v254, 12
	v_readlane_b32 s53, v254, 13
	v_cndmask_b32_e32 v0, v0, v24, vcc
	v_readlane_b32 s54, v254, 14
	v_readlane_b32 s55, v254, 15
	v_readlane_b32 s56, v254, 16
	v_readlane_b32 s57, v254, 17
	v_readlane_b32 s58, v254, 18
	v_readlane_b32 s59, v254, 19
	v_readlane_b32 s60, v254, 20
	v_readlane_b32 s61, v254, 21
	v_lshlrev_b32_e32 v4, 2, v0
	v_lshlrev_b32_e32 v20, 5, v181
	v_readlane_b32 s62, v254, 22
	v_readlane_b32 s63, v254, 23
	v_readlane_b32 s64, v254, 24
	v_readlane_b32 s65, v254, 25
	s_mov_b64 s[52:53], s[56:57]
	global_load_dwordx4 v[0:3], v4, s[44:45]
	s_nop 0
	global_load_dwordx4 v[4:7], v4, s[44:45] offset:16
	s_nop 0
	global_load_dwordx4 v[8:11], v20, s[52:53]
	global_load_dwordx4 v[12:15], v20, s[52:53] offset:16
	global_load_dwordx4 v[16:19], v20, s[44:45] offset:2048
	s_nop 0
	global_load_dwordx4 v[20:23], v20, s[44:45] offset:2064
	v_readlane_b32 s12, v254, 29
	v_readlane_b32 s13, v254, 30
	s_mov_b32 s28, s12
	s_ashr_i32 s29, s12, 31
	s_mul_hi_i32 s13, s12, 0x300
	s_mulk_i32 s12, 0x300
	v_and_b32_e32 v25, 7, v210
	s_movk_i32 s6, 0x63f
	s_movk_i32 s8, 0x680
	s_add_u32 s12, s72, s12
	v_cmp_eq_u32_e64 s[2:3], 0, v25
	v_cmp_lt_u32_e64 s[6:7], s6, v24
	v_cmp_gt_u32_e64 s[8:9], s8, v24
	v_lshlrev_b32_e32 v24, 4, v181
	v_mov_b32_e32 v25, 0
	s_addc_u32 s13, s73, s13
	v_lshl_add_u64 v[26:27], s[12:13], 0, v[24:25]
	s_mov_b64 s[12:13], 0x3d00000
	v_lshl_add_u64 v[42:43], v[26:27], 0, s[12:13]
	s_ashr_i32 s35, s34, 31
	s_lshl_b64 s[12:13], s[28:29], 5
	v_lshrrev_b32_e32 v26, 1, v181
	s_add_u32 s12, s72, s12
	v_and_b32_e32 v26, 28, v26
	v_mov_b32_e32 v27, v25
	s_addc_u32 s13, s73, s13
	v_lshl_add_u64 v[26:27], s[12:13], 0, v[26:27]
	s_mov_b64 s[12:13], 0x2a80000
	v_lshl_add_u64 v[44:45], v[26:27], 0, s[12:13]
	s_lshl_b64 s[20:21], s[34:35], 5
	s_lshl_b64 s[12:13], s[28:29], 12
	s_add_u32 s12, s72, s12
	s_addc_u32 s13, s73, s13
	v_lshl_add_u64 v[40:41], s[42:43], 0, v[24:25]
	v_lshl_add_u64 v[24:25], s[12:13], 0, v[24:25]
	s_mov_b64 s[12:13], 0x7d00400
	v_lshl_add_u64 v[46:47], v[24:25], 0, s[12:13]
	s_mov_b32 s12, s28
	v_readlane_b32 s66, v254, 26
	v_readlane_b32 s67, v254, 27
	v_cmp_lt_u32_e64 s[0:1], 35, v181
	v_cmp_gt_u32_e64 s[4:5], 48, v181
	s_mul_hi_i32 s19, s34, 0x300
	s_mul_i32 s18, s34, 0x300
	s_lshl_b64 s[22:23], s[34:35], 12
	s_mov_b32 s14, 0xffff0000
	v_writelane_b32 v254, s12, 29
	s_mov_b64 s[54:55], s[58:59]
	s_mov_b64 s[56:57], s[60:61]
	s_mov_b64 s[58:59], s[62:63]
	s_mov_b64 s[60:61], s[64:65]
	v_writelane_b32 v254, s13, 30
	s_and_b32 s12, s28, 0xfff
	s_cmp_lg_u32 s12, 0
	s_cselect_b64 s[12:13], -1, 0
	v_cndmask_b32_e64 v80, 0, 1, s[12:13]
	v_mov_b32_e32 v81, s29
	v_sub_co_u32_e64 v80, s[12:13], s28, v80
	global_load_dwordx4 v[60:63], v[46:47], off
	s_nop 0
	v_subbrev_co_u32_e64 v81, s[12:13], 0, v81, s[12:13]
	v_lshlrev_b64 v[80:81], 12, v[80:81]
	v_lshl_add_u64 v[78:79], v[40:41], 0, v[80:81]
	global_load_dwordx4 v[64:67], v[78:79], off offset:1024
	v_mov_b32_e32 v68, 0
	v_mov_b32_e32 v69, 0
	v_mov_b32_e32 v70, 0
	v_mov_b32_e32 v71, 0
	v_mov_b32_e32 v72, 0
	v_mov_b32_e32 v73, 0
	v_mov_b32_e32 v74, 0
	v_mov_b32_e32 v75, 0
	s_and_saveexec_b64 s[12:13], vcc
	s_cbranch_execz .Lmy_p2_a
	global_load_dwordx4 v[68:71], v[46:47], off offset:2048
	global_load_dwordx4 v[72:75], v[78:79], off offset:3072
.Lmy_p2_a:
	s_or_b64 exec, exec, s[12:13]
	s_waitcnt vmcnt(0)
	s_branch .LBB0_376

.LBB0_376:
	s_and_b32 s12, s28, 0xfff
	s_cmp_lg_u32 s12, 0
	s_cselect_b64 s[38:39], -1, 0
	s_waitcnt vmcnt(1)
	v_mov_b64_e32 v[36:37], v[60:61]
	v_mov_b64_e32 v[38:39], v[62:63]
	v_mov_b64_e32 v[32:33], v[64:65]
	v_mov_b64_e32 v[34:35], v[66:67]
	v_mov_b64_e32 v[28:29], v[68:69]
	v_mov_b64_e32 v[30:31], v[70:71]
	v_mov_b64_e32 v[24:25], v[72:73]
	v_mov_b64_e32 v[26:27], v[74:75]
	s_add_u32 s98, s28, s34
	s_addc_u32 s99, s29, s35
	s_cmp_lt_i32 s98, 0x8000
	s_cbranch_scc0 .Lmy_p2_skip
	s_and_b32 s12, s98, 0xfff
	s_cmp_lg_u32 s12, 0
	s_cselect_b64 s[12:13], -1, 0
	v_cndmask_b32_e64 v80, 0, 1, s[12:13]
	v_mov_b32_e32 v81, s99
	v_lshl_add_u64 v[76:77], v[46:47], 0, s[22:23]
	v_sub_co_u32_e64 v80, s[12:13], s98, v80
	global_load_dwordx4 v[60:63], v[76:77], off
	s_nop 0
	v_subbrev_co_u32_e64 v81, s[12:13], 0, v81, s[12:13]
	v_lshlrev_b64 v[80:81], 12, v[80:81]
	v_lshl_add_u64 v[78:79], v[40:41], 0, v[80:81]
	global_load_dwordx4 v[64:67], v[78:79], off offset:1024
	v_mov_b32_e32 v68, 0
	v_mov_b32_e32 v69, 0
	v_mov_b32_e32 v70, 0
	v_mov_b32_e32 v71, 0
	v_mov_b32_e32 v72, 0
	v_mov_b32_e32 v73, 0
	v_mov_b32_e32 v74, 0
	v_mov_b32_e32 v75, 0
	s_and_saveexec_b64 s[12:13], vcc
	s_cbranch_execz .Lmy_p2_b
	global_load_dwordx4 v[68:71], v[76:77], off offset:2048
	global_load_dwordx4 v[72:75], v[78:79], off offset:3072

.Lmy_p2_skip:
	v_cndmask_b32_e64 v48, 0, 1.0, s[38:39]
	v_lshlrev_b32_e32 v49, 16, v36
	v_and_b32_e32 v36, 0xffff0000, v36
	v_lshlrev_b32_e32 v53, 16, v32
	v_and_b32_e32 v32, 0xffff0000, v32
	v_fma_f32 v32, v48, v32, -v36
	v_lshlrev_b32_e32 v50, 16, v37
	v_lshlrev_b32_e32 v54, 16, v33
	v_fma_f32 v53, v48, v53, -v49
	v_fmac_f32_e32 v36, v32, v17
	v_and_b32_e32 v37, 0xffff0000, v37
	v_and_b32_e32 v33, 0xffff0000, v33
	v_fmac_f32_e32 v49, v53, v16
	v_mul_f32_e32 v32, v36, v9
	v_fma_f32 v36, v48, v54, -v50
	v_mul_f32_e32 v49, v49, v8
	v_mul_f32_e32 v32, v32, v32
	v_fmac_f32_e32 v50, v36, v18
	v_fma_f32 v33, v48, v33, -v37
	v_fmac_f32_e32 v32, v49, v49
	v_mul_f32_e32 v36, v50, v10
	v_fmac_f32_e32 v37, v33, v19
	v_lshlrev_b32_e32 v51, 16, v38
	v_lshlrev_b32_e32 v55, 16, v34
	v_fmac_f32_e32 v32, v36, v36
	v_mul_f32_e32 v33, v37, v11
	v_fmac_f32_e32 v32, v33, v33
	v_fma_f32 v33, v48, v55, -v51
	v_fmac_f32_e32 v51, v33, v20
	v_and_b32_e32 v38, 0xffff0000, v38
	v_and_b32_e32 v34, 0xffff0000, v34
	v_mul_f32_e32 v33, v51, v12
	v_fmac_f32_e32 v32, v33, v33
	v_fma_f32 v33, v48, v34, -v38
	v_fmac_f32_e32 v38, v33, v21
	v_lshlrev_b32_e32 v52, 16, v39
	v_lshlrev_b32_e32 v56, 16, v35
	v_mul_f32_e32 v33, v38, v13
	v_fmac_f32_e32 v32, v33, v33
	v_fma_f32 v33, v48, v56, -v52
	v_fmac_f32_e32 v52, v33, v22
	v_and_b32_e32 v39, 0xffff0000, v39
	v_and_b32_e32 v35, 0xffff0000, v35
	v_mul_f32_e32 v33, v52, v14
	v_fmac_f32_e32 v32, v33, v33
	v_fma_f32 v33, v48, v35, -v39
	v_fmac_f32_e32 v39, v33, v23
	v_mul_f32_e32 v33, v39, v15
	v_fmac_f32_e32 v32, v33, v33
	s_nop 1
	v_add_f32_dpp v32, v32, v32 quad_perm:[1,0,3,2] row_mask:0xf bank_mask:0xf bound_ctrl:1
	s_nop 1
	v_add_f32_dpp v32, v32, v32 quad_perm:[2,3,0,1] row_mask:0xf bank_mask:0xf bound_ctrl:1
	s_nop 1
	v_mov_b32_dpp v33, v32 row_half_mirror row_mask:0xf bank_mask:0xf bound_ctrl:1
	s_and_saveexec_b64 s[12:13], s[2:3]
	s_cbranch_execz .LBB0_380
	v_add_f32_e32 v32, v32, v33
	v_max_f32_e32 v32, 0x179abe15, v32
	v_rsq_f32_e32 v32, v32
	global_store_dword v[44:45], v32, off
